# plus_rglru_conv_batch_and_addr_strength_reduction
# baseline (speedup 1.0000x reference)
; DEVI unsigned pk_bf16(float lo, float hi) { unsigned r; asm("v_cvt_pk_bf16_f32 %0, %1, %2" : "=v"(r) : "v"(lo), "v"(hi)); return r; }
; DEVI float bf_lo(unsigned u) { return __uint_as_float(u << 16); }
; DEVI float bf_hi(unsigned u) { return __uint_as_float(u & 0xffff0000u); }
; DEVI float bf2f(bf16_t v) { return __uint_as_float(((unsigned)v) << 16); }
; DEVI bf16_t f2bf(float f) { return (bf16_t)(pk_bf16(f, 0.f) & 0xffffu); }
; DEVI float sigmoidf_(float x) { return __builtin_amdgcn_rcpf(1.0f + __builtin_amdgcn_exp2f(-x * LOG2E)); }
; __device__ __forceinline__ void rglru_item8(const Params& p, unsigned char* lds, int item) {
;     ...
;     {
;       const int tr = tid >> 3, cp = tid & 7;
; #pragma unroll
;       for (int c8 = 0; c8 < 2; ++c8) {
;         const int c0 = cp * 16 + c8 * 8; float o[8];
; #pragma unroll
;         for (int j = 0; j < 8; ++j) o[j] = cw[512 + c0 + j];
; #pragma unroll
;         for (int k = 0; k < 4; ++k) { const uint4 xv = *(const uint4*)(raw + (tr + k) * 136 + c0); const float* wp = cw + k * 128 + c0;
;           o[0] += wp[0] * bf_lo(xv.x); o[1] += wp[1] * bf_hi(xv.x); o[2] += wp[2] * bf_lo(xv.y); o[3] += wp[3] * bf_hi(xv.y);
;           o[4] += wp[4] * bf_lo(xv.z); o[5] += wp[5] * bf_hi(xv.z); o[6] += wp[6] * bf_lo(xv.w); o[7] += wp[7] * bf_hi(xv.w); }
;         *(uint4*)(xcA + tr * 136 + c0) = make_uint4(pk_bf16(o[0], o[1]), pk_bf16(o[2], o[3]), pk_bf16(o[4], o[5]), pk_bf16(o[6], o[7]));
;         if ((cp >> 2) == h2) {
; #pragma unroll
;           for (int j = 0; j < 8; ++j) xcF[tr * 65 + (c0 - 64 * h2) + j] = o[j]; }
;     ...
;       for (int k = 0; k < 8; ++k) {
;         const float hv = Lk[k] + Pk[k] * hin; const int t = 64 * ti + 8 * seg + k;
;         if (k == 7 && seg == 7) hst[(cur ^ 1) * 64 + j] = hv;
;         if (t < T) { bf16_t* gp = Z + (size_t)(b * T + t) * LDZE + 4096 + g * 128 + h2 * 64 + j; const float x = bf2f(gbv[k]);
;           const float ge = x * sigmoidf_(1.5957691216057308f * (x + 0.044715f * x * x * x)); *gp = f2bf(hv * ge); }
.LBB0_543:
	s_waitcnt lgkmcnt(0)
	s_barrier
	s_add_i32 s98, s89, s75
	s_mul_hi_i32 s99, s98, 0x2800
	s_mulk_i32 s98, 0x2800
	s_add_u32 s98, s60, s98
	s_addc_u32 s99, s61, s99
	s_lshl_b32 s100, s73, 1
	s_add_u32 s98, s98, s100
	s_addc_u32 s99, s99, 0
	s_lshl_b32 s100, s72, 1
	s_add_u32 s98, s98, s100
	s_addc_u32 s99, s99, 0
	s_waitcnt vmcnt(0)
	ds_write_b128 v140, v[64:67] offset:816
	ds_write_b128 v140, v[68:71] offset:9520
	s_waitcnt lgkmcnt(0)
	s_barrier
	ds_read_b128 v[216:219], v142
	ds_read_b128 v[220:223], v142 offset:272
	ds_read_b128 v[224:227], v142 offset:544
	ds_read_b128 v[228:231], v142 offset:816
	ds_read_b128 v[184:187], v141
	ds_read_b128 v[188:191], v141 offset:16
	ds_read_b128 v[192:195], v141 offset:512
	ds_read_b128 v[196:199], v141 offset:528
	ds_read_b128 v[200:203], v141 offset:1024
	ds_read_b128 v[204:207], v141 offset:1040
	ds_read_b128 v[208:211], v141 offset:1536
	ds_read_b128 v[80:83], v141 offset:1552
	ds_read_b128 v[84:87], v141 offset:2048
	ds_read_b128 v[88:91], v141 offset:2064
	ds_read_b128 v[232:235], v142 offset:16
	ds_read_b128 v[236:239], v142 offset:288
	ds_read_b128 v[240:243], v142 offset:560
	ds_read_b128 v[244:247], v142 offset:832
	s_waitcnt lgkmcnt(4)
	v_lshlrev_b32_e32 v250, 16, v216
	v_and_b32_e32 v251, 0xffff0000, v216
	v_pk_fma_f32 v[92:93], v[184:185], v[250:251], v[84:85]
	v_lshlrev_b32_e32 v250, 16, v220
	v_and_b32_e32 v251, 0xffff0000, v220
	v_pk_fma_f32 v[92:93], v[192:193], v[250:251], v[92:93]
	v_lshlrev_b32_e32 v250, 16, v224
	v_and_b32_e32 v251, 0xffff0000, v224
	v_pk_fma_f32 v[92:93], v[200:201], v[250:251], v[92:93]
	v_lshlrev_b32_e32 v250, 16, v228
	v_and_b32_e32 v251, 0xffff0000, v228
	v_pk_fma_f32 v[92:93], v[208:209], v[250:251], v[92:93]
	v_lshlrev_b32_e32 v250, 16, v217
	v_and_b32_e32 v251, 0xffff0000, v217
	v_pk_fma_f32 v[94:95], v[186:187], v[250:251], v[86:87]
	v_lshlrev_b32_e32 v250, 16, v221
	v_and_b32_e32 v251, 0xffff0000, v221
	v_pk_fma_f32 v[94:95], v[194:195], v[250:251], v[94:95]
	v_lshlrev_b32_e32 v250, 16, v225
	v_and_b32_e32 v251, 0xffff0000, v225
	v_pk_fma_f32 v[94:95], v[202:203], v[250:251], v[94:95]
	v_lshlrev_b32_e32 v250, 16, v229
	v_and_b32_e32 v251, 0xffff0000, v229
	v_pk_fma_f32 v[94:95], v[210:211], v[250:251], v[94:95]
	v_lshlrev_b32_e32 v250, 16, v218
	v_and_b32_e32 v251, 0xffff0000, v218
	v_pk_fma_f32 v[106:107], v[188:189], v[250:251], v[88:89]
	v_lshlrev_b32_e32 v250, 16, v222
	v_and_b32_e32 v251, 0xffff0000, v222
	v_pk_fma_f32 v[106:107], v[196:197], v[250:251], v[106:107]
	v_lshlrev_b32_e32 v250, 16, v226
	v_and_b32_e32 v251, 0xffff0000, v226
	v_pk_fma_f32 v[106:107], v[204:205], v[250:251], v[106:107]
	v_lshlrev_b32_e32 v250, 16, v230
	v_and_b32_e32 v251, 0xffff0000, v230
	v_pk_fma_f32 v[106:107], v[80:81], v[250:251], v[106:107]
	v_lshlrev_b32_e32 v250, 16, v219
	v_and_b32_e32 v251, 0xffff0000, v219
	v_pk_fma_f32 v[248:249], v[190:191], v[250:251], v[90:91]
	v_lshlrev_b32_e32 v250, 16, v223
	v_and_b32_e32 v251, 0xffff0000, v223
	v_pk_fma_f32 v[248:249], v[198:199], v[250:251], v[248:249]
	v_lshlrev_b32_e32 v250, 16, v227
	v_and_b32_e32 v251, 0xffff0000, v227
	v_pk_fma_f32 v[248:249], v[206:207], v[250:251], v[248:249]
	v_lshlrev_b32_e32 v250, 16, v231
	v_and_b32_e32 v251, 0xffff0000, v231
	v_pk_fma_f32 v[248:249], v[82:83], v[250:251], v[248:249]
	v_cvt_pk_bf16_f32 v88, v92, v93
	v_cvt_pk_bf16_f32 v89, v94, v95
	v_cvt_pk_bf16_f32 v90, v106, v107
	v_cvt_pk_bf16_f32 v91, v248, v249
	ds_write_b128 v142, v[88:91] offset:18224
	s_and_saveexec_b64 s[6:7], s[2:3]
	s_cbranch_execz .Lrgc_a1
	v_add_u32_e32 v252, 0x8b30, v143
	ds_write2_b32 v252, v92, v93 offset1:1
	v_add_u32_e32 v252, 0x8b38, v143
	ds_write2_b32 v252, v94, v95 offset1:1
	v_add_u32_e32 v252, 0x8b40, v143
	ds_write2_b32 v252, v106, v107 offset1:1
	v_add_u32_e32 v252, 0x8b48, v143
	ds_write2_b32 v252, v248, v249 offset1:1
.Lrgc_a1:
	s_or_b64 exec, exec, s[6:7]
	ds_read_b128 v[184:187], v144
	ds_read_b128 v[188:191], v144 offset:16
	ds_read_b128 v[192:195], v144 offset:512
	ds_read_b128 v[196:199], v144 offset:528
	ds_read_b128 v[200:203], v144 offset:1024
	ds_read_b128 v[204:207], v144 offset:1040
	ds_read_b128 v[208:211], v144 offset:1536
	ds_read_b128 v[80:83], v144 offset:1552
	ds_read_b128 v[84:87], v144 offset:2048
	ds_read_b128 v[88:91], v141 offset:2096
	s_waitcnt lgkmcnt(0)
	v_lshlrev_b32_e32 v250, 16, v232
	v_and_b32_e32 v251, 0xffff0000, v232
	v_pk_fma_f32 v[92:93], v[184:185], v[250:251], v[84:85]
	v_lshlrev_b32_e32 v250, 16, v236
	v_and_b32_e32 v251, 0xffff0000, v236
	v_pk_fma_f32 v[92:93], v[192:193], v[250:251], v[92:93]
	v_lshlrev_b32_e32 v250, 16, v240
	v_and_b32_e32 v251, 0xffff0000, v240
	v_pk_fma_f32 v[92:93], v[200:201], v[250:251], v[92:93]
	v_lshlrev_b32_e32 v250, 16, v244
	v_and_b32_e32 v251, 0xffff0000, v244
	v_pk_fma_f32 v[92:93], v[208:209], v[250:251], v[92:93]
	v_lshlrev_b32_e32 v250, 16, v233
	v_and_b32_e32 v251, 0xffff0000, v233
	v_pk_fma_f32 v[94:95], v[186:187], v[250:251], v[86:87]
	v_lshlrev_b32_e32 v250, 16, v237
	v_and_b32_e32 v251, 0xffff0000, v237
	v_pk_fma_f32 v[94:95], v[194:195], v[250:251], v[94:95]
	v_lshlrev_b32_e32 v250, 16, v241
	v_and_b32_e32 v251, 0xffff0000, v241
	v_pk_fma_f32 v[94:95], v[202:203], v[250:251], v[94:95]
	v_lshlrev_b32_e32 v250, 16, v245
	v_and_b32_e32 v251, 0xffff0000, v245
	v_pk_fma_f32 v[94:95], v[210:211], v[250:251], v[94:95]
	v_lshlrev_b32_e32 v250, 16, v234
	v_and_b32_e32 v251, 0xffff0000, v234
	v_pk_fma_f32 v[106:107], v[188:189], v[250:251], v[88:89]
	v_lshlrev_b32_e32 v250, 16, v238
	v_and_b32_e32 v251, 0xffff0000, v238
	v_pk_fma_f32 v[106:107], v[196:197], v[250:251], v[106:107]
	v_lshlrev_b32_e32 v250, 16, v242
	v_and_b32_e32 v251, 0xffff0000, v242
	v_pk_fma_f32 v[106:107], v[204:205], v[250:251], v[106:107]
	v_lshlrev_b32_e32 v250, 16, v246
	v_and_b32_e32 v251, 0xffff0000, v246
	v_pk_fma_f32 v[106:107], v[80:81], v[250:251], v[106:107]
	v_lshlrev_b32_e32 v250, 16, v235
	v_and_b32_e32 v251, 0xffff0000, v235
	v_pk_fma_f32 v[248:249], v[190:191], v[250:251], v[90:91]
	v_lshlrev_b32_e32 v250, 16, v239
	v_and_b32_e32 v251, 0xffff0000, v239
	v_pk_fma_f32 v[248:249], v[198:199], v[250:251], v[248:249]
	v_lshlrev_b32_e32 v250, 16, v243
	v_and_b32_e32 v251, 0xffff0000, v243
	v_pk_fma_f32 v[248:249], v[206:207], v[250:251], v[248:249]
	v_lshlrev_b32_e32 v250, 16, v247
	v_and_b32_e32 v251, 0xffff0000, v247
	v_pk_fma_f32 v[248:249], v[82:83], v[250:251], v[248:249]
	v_cvt_pk_bf16_f32 v88, v92, v93
	v_cvt_pk_bf16_f32 v89, v94, v95
	v_cvt_pk_bf16_f32 v90, v106, v107
	v_cvt_pk_bf16_f32 v91, v248, v249
	ds_write_b128 v142, v[88:91] offset:18240
	s_and_saveexec_b64 s[6:7], s[2:3]
	s_cbranch_execz .LBB0_547
	v_add_u32_e32 v252, 0x8b50, v143
	ds_write2_b32 v252, v92, v93 offset1:1
	v_add_u32_e32 v252, 0x8b58, v143
	ds_write2_b32 v252, v94, v95 offset1:1
	v_add_u32_e32 v252, 0x8b60, v143
	ds_write2_b32 v252, v106, v107 offset1:1
	v_add_u32_e32 v252, 0x8b68, v143
	ds_write2_b32 v252, v248, v249 offset1:1

; DEVI float bf2f(bf16_t v) { return __uint_as_float(((unsigned)v) << 16); }
; DEVI bf16_t f2bf(float f) { return (bf16_t)(pk_bf16(f, 0.f) & 0xffffu); }
; DEVI float sigmoidf_(float x) { return __builtin_amdgcn_rcpf(1.0f + __builtin_amdgcn_exp2f(-x * LOG2E)); }
; __device__ __forceinline__ void rglru_item8(const Params& p, unsigned char* lds, int item) {
;     ...
;       for (int k = 0; k < 8; ++k) {
;         const float hv = Lk[k] + Pk[k] * hin; const int t = 64 * ti + 8 * seg + k;
;         if (k == 7 && seg == 7) hst[(cur ^ 1) * 64 + j] = hv;
;         if (t < T) { bf16_t* gp = Z + (size_t)(b * T + t) * LDZE + 4096 + g * 128 + h2 * 64 + j; const float x = bf2f(gbv[k]);
;           const float ge = x * sigmoidf_(1.5957691216057308f * (x + 0.044715f * x * x * x)); *gp = f2bf(hv * ge); }
.LBB0_596:
	v_lshlrev_b32_e32 v82, 16, v122
	v_mul_f32_e32 v105, 0x3d372713, v82
	v_mul_f32_e32 v105, v105, v82
	v_fma_f32 v105, v105, v82, v82
	v_mul_f32_e32 v105, 0x3fcc422a, v105
	v_mul_f32_e32 v105, 0xbfb8aa3b, v105
	v_exp_f32_e32 v105, v105
	s_nop 0
	v_add_f32_e32 v105, 1.0, v105
	v_rcp_f32_e32 v184, v105
	s_nop 0
	s_add_u32 s20, s98, 0x0
	v_mov_b32_e32 v185, v80
	s_addc_u32 s21, s99, 0
	v_mov_b32_e32 v105, v96
	s_waitcnt lgkmcnt(0)
	v_pk_mul_f32 v[184:185], v[184:185], v[82:83]
	v_lshl_add_u64 v[186:187], s[20:21], 0, v[104:105]
	v_add_f32_e32 v80, v92, v185
	v_mul_f32_e32 v80, v184, v80
	v_add_co_u32_e32 v184, vcc, 0x2000, v186
	v_cvt_pk_bf16_f32 v80, v80, v96
	s_nop 1
	v_addc_co_u32_e32 v185, vcc, 0, v187, vcc
	global_store_short v[184:185], v80, off
	s_add_i32 s20, s33, 1
	s_cmpk_gt_i32 s20, 0x100f
	s_cbranch_scc0 .LBB0_613

; DEVI float bf2f(bf16_t v) { return __uint_as_float(((unsigned)v) << 16); }
; DEVI bf16_t f2bf(float f) { return (bf16_t)(pk_bf16(f, 0.f) & 0xffffu); }
; DEVI float sigmoidf_(float x) { return __builtin_amdgcn_rcpf(1.0f + __builtin_amdgcn_exp2f(-x * LOG2E)); }
; __device__ __forceinline__ void rglru_item8(const Params& p, unsigned char* lds, int item) {
;     ...
;       for (int k = 0; k < 8; ++k) {
;         const float hv = Lk[k] + Pk[k] * hin; const int t = 64 * ti + 8 * seg + k;
;         if (k == 7 && seg == 7) hst[(cur ^ 1) * 64 + j] = hv;
;         if (t < T) { bf16_t* gp = Z + (size_t)(b * T + t) * LDZE + 4096 + g * 128 + h2 * 64 + j; const float x = bf2f(gbv[k]);
;           const float ge = x * sigmoidf_(1.5957691216057308f * (x + 0.044715f * x * x * x)); *gp = f2bf(hv * ge); }
.LBB0_598:
	v_lshlrev_b32_e32 v82, 16, v124
	v_mul_f32_e32 v80, 0x3d372713, v82
	v_mul_f32_e32 v80, v80, v82
	v_fma_f32 v80, v80, v82, v82
	v_mul_f32_e32 v80, 0x3fcc422a, v80
	v_mul_f32_e32 v80, 0xbfb8aa3b, v80
	v_exp_f32_e32 v80, v80
	s_nop 0
	v_add_f32_e32 v80, 1.0, v80
	v_rcp_f32_e32 v90, v80
	s_nop 0
	s_add_u32 s20, s98, 0x5000
	s_addc_u32 s21, s99, 0
	v_mov_b32_e32 v105, v96
	s_waitcnt lgkmcnt(0)
	v_pk_mul_f32 v[90:91], v[90:91], v[82:83]
	v_lshl_add_u64 v[92:93], s[20:21], 0, v[104:105]
	v_add_f32_e32 v80, v88, v91
	v_mul_f32_e32 v80, v90, v80
	v_add_co_u32_e32 v90, vcc, 0x2000, v92
	v_cvt_pk_bf16_f32 v80, v80, v96
	s_nop 1
	v_addc_co_u32_e32 v91, vcc, 0, v93, vcc
	global_store_short v[90:91], v80, off
	s_add_i32 s20, s33, 3
	s_cmpk_gt_i32 s20, 0x100f
	s_cbranch_scc0 .LBB0_615

; DEVI float bf2f(bf16_t v) { return __uint_as_float(((unsigned)v) << 16); }
; DEVI bf16_t f2bf(float f) { return (bf16_t)(pk_bf16(f, 0.f) & 0xffffu); }
; DEVI float sigmoidf_(float x) { return __builtin_amdgcn_rcpf(1.0f + __builtin_amdgcn_exp2f(-x * LOG2E)); }
; __device__ __forceinline__ void rglru_item8(const Params& p, unsigned char* lds, int item) {
;     ...
;       for (int k = 0; k < 8; ++k) {
;         const float hv = Lk[k] + Pk[k] * hin; const int t = 64 * ti + 8 * seg + k;
;         if (k == 7 && seg == 7) hst[(cur ^ 1) * 64 + j] = hv;
;         if (t < T) { bf16_t* gp = Z + (size_t)(b * T + t) * LDZE + 4096 + g * 128 + h2 * 64 + j; const float x = bf2f(gbv[k]);
;           const float ge = x * sigmoidf_(1.5957691216057308f * (x + 0.044715f * x * x * x)); *gp = f2bf(hv * ge); }
.LBB0_600:
	v_lshlrev_b32_e32 v82, 16, v129
	v_mul_f32_e32 v80, 0x3d372713, v82
	v_mul_f32_e32 v80, v80, v82
	v_fma_f32 v80, v80, v82, v82
	v_mul_f32_e32 v80, 0x3fcc422a, v80
	v_mul_f32_e32 v80, 0xbfb8aa3b, v80
	v_exp_f32_e32 v80, v80
	s_nop 0
	v_add_f32_e32 v80, 1.0, v80
	v_rcp_f32_e32 v86, v80
	s_nop 0
	s_add_u32 s20, s98, 0xa000
	s_addc_u32 s21, s99, 0
	v_mov_b32_e32 v105, v96
	s_waitcnt lgkmcnt(0)
	v_pk_mul_f32 v[86:87], v[86:87], v[82:83]
	v_lshl_add_u64 v[88:89], s[20:21], 0, v[104:105]
	v_add_f32_e32 v80, v84, v87
	v_mul_f32_e32 v80, v86, v80
	v_add_co_u32_e32 v86, vcc, 0x2000, v88
	v_cvt_pk_bf16_f32 v80, v80, v96
	s_nop 1
	v_addc_co_u32_e32 v87, vcc, 0, v89, vcc
	global_store_short v[86:87], v80, off
	s_add_i32 s20, s33, 5
	s_cmpk_gt_i32 s20, 0x100f
	s_cbranch_scc0 .LBB0_617

; DEVI float bf2f(bf16_t v) { return __uint_as_float(((unsigned)v) << 16); }
; DEVI bf16_t f2bf(float f) { return (bf16_t)(pk_bf16(f, 0.f) & 0xffffu); }
; DEVI float sigmoidf_(float x) { return __builtin_amdgcn_rcpf(1.0f + __builtin_amdgcn_exp2f(-x * LOG2E)); }
; __device__ __forceinline__ void rglru_item8(const Params& p, unsigned char* lds, int item) {
;     ...
;       for (int k = 0; k < 8; ++k) {
;         const float hv = Lk[k] + Pk[k] * hin; const int t = 64 * ti + 8 * seg + k;
;         if (k == 7 && seg == 7) hst[(cur ^ 1) * 64 + j] = hv;
;         if (t < T) { bf16_t* gp = Z + (size_t)(b * T + t) * LDZE + 4096 + g * 128 + h2 * 64 + j; const float x = bf2f(gbv[k]);
;           const float ge = x * sigmoidf_(1.5957691216057308f * (x + 0.044715f * x * x * x)); *gp = f2bf(hv * ge); }
.LBB0_602:
	v_lshlrev_b32_e32 v82, 16, v133
	v_mul_f32_e32 v80, 0x3d372713, v82
	v_mul_f32_e32 v80, v80, v82
	v_fma_f32 v80, v80, v82, v82
	v_mul_f32_e32 v80, 0x3fcc422a, v80
	v_mul_f32_e32 v80, 0xbfb8aa3b, v80
	v_exp_f32_e32 v80, v80
	s_nop 0
	v_add_f32_e32 v80, 1.0, v80
	v_rcp_f32_e32 v80, v80
	s_nop 0
	s_add_u32 s20, s98, 0xf000
	s_waitcnt lgkmcnt(0)
	v_pk_mul_f32 v[80:81], v[80:81], v[82:83]
	s_addc_u32 s21, s99, 0
	v_mov_b32_e32 v105, v96
	v_add_f32_e32 v81, v95, v81
	v_lshl_add_u64 v[84:85], s[20:21], 0, v[104:105]
	v_mul_f32_e32 v80, v80, v81
	v_cvt_pk_bf16_f32 v82, v80, v96
	v_add_co_u32_e32 v80, vcc, 0x2000, v84
	s_nop 1
	v_addc_co_u32_e32 v81, vcc, 0, v85, vcc
	global_store_short v[80:81], v82, off

; DEVI float bf2f(bf16_t v) { return __uint_as_float(((unsigned)v) << 16); }
; DEVI bf16_t f2bf(float f) { return (bf16_t)(pk_bf16(f, 0.f) & 0xffffu); }
; DEVI float sigmoidf_(float x) { return __builtin_amdgcn_rcpf(1.0f + __builtin_amdgcn_exp2f(-x * LOG2E)); }
; __device__ __forceinline__ void rglru_item8(const Params& p, unsigned char* lds, int item) {
;     ...
;       for (int k = 0; k < 8; ++k) {
;         const float hv = Lk[k] + Pk[k] * hin; const int t = 64 * ti + 8 * seg + k;
;         if (k == 7 && seg == 7) hst[(cur ^ 1) * 64 + j] = hv;
;         if (t < T) { bf16_t* gp = Z + (size_t)(b * T + t) * LDZE + 4096 + g * 128 + h2 * 64 + j; const float x = bf2f(gbv[k]);
;           const float ge = x * sigmoidf_(1.5957691216057308f * (x + 0.044715f * x * x * x)); *gp = f2bf(hv * ge); }
.LBB0_613:
	v_lshlrev_b32_e32 v82, 16, v121
	v_mul_f32_e32 v80, 0x3d372713, v82
	v_mul_f32_e32 v80, v80, v82
	v_fma_f32 v80, v80, v82, v82
	v_mul_f32_e32 v80, 0x3fcc422a, v80
	v_mul_f32_e32 v80, 0xbfb8aa3b, v80
	v_exp_f32_e32 v80, v80
	s_nop 0
	v_add_f32_e32 v80, 1.0, v80
	v_rcp_f32_e32 v92, v80
	s_nop 0
	s_add_u32 s20, s98, 0x2800
	s_addc_u32 s21, s99, 0
	v_mov_b32_e32 v105, v96
	s_waitcnt lgkmcnt(0)
	v_pk_mul_f32 v[92:93], v[92:93], v[82:83]
	v_lshl_add_u64 v[184:185], s[20:21], 0, v[104:105]
	v_add_f32_e32 v80, v90, v93
	v_mul_f32_e32 v80, v92, v80
	v_add_co_u32_e32 v92, vcc, 0x2000, v184
	v_cvt_pk_bf16_f32 v80, v80, v96
	s_nop 1
	v_addc_co_u32_e32 v93, vcc, 0, v185, vcc
	global_store_short v[92:93], v80, off
	s_add_i32 s20, s33, 2
	s_cmpk_gt_i32 s20, 0x100f
	s_cbranch_scc0 .LBB0_598

; DEVI float bf2f(bf16_t v) { return __uint_as_float(((unsigned)v) << 16); }
; DEVI bf16_t f2bf(float f) { return (bf16_t)(pk_bf16(f, 0.f) & 0xffffu); }
; DEVI float sigmoidf_(float x) { return __builtin_amdgcn_rcpf(1.0f + __builtin_amdgcn_exp2f(-x * LOG2E)); }
; __device__ __forceinline__ void rglru_item8(const Params& p, unsigned char* lds, int item) {
;     ...
;         const float hv = Lk[k] + Pk[k] * hin; const int t = 64 * ti + 8 * seg + k;
;         if (k == 7 && seg == 7) hst[(cur ^ 1) * 64 + j] = hv;
;         if (t < T) { bf16_t* gp = Z + (size_t)(b * T + t) * LDZE + 4096 + g * 128 + h2 * 64 + j; const float x = bf2f(gbv[k]);
;           const float ge = x * sigmoidf_(1.5957691216057308f * (x + 0.044715f * x * x * x)); *gp = f2bf(hv * ge); }
.LBB0_615:
	v_lshlrev_b32_e32 v82, 16, v123
	v_mul_f32_e32 v80, 0x3d372713, v82
	v_mul_f32_e32 v80, v80, v82
	v_fma_f32 v80, v80, v82, v82
	v_mul_f32_e32 v80, 0x3fcc422a, v80
	v_mul_f32_e32 v80, 0xbfb8aa3b, v80
	v_exp_f32_e32 v80, v80
	s_nop 0
	v_add_f32_e32 v80, 1.0, v80
	v_rcp_f32_e32 v88, v80
	s_nop 0
	s_add_u32 s20, s98, 0x7800
	s_addc_u32 s21, s99, 0
	v_mov_b32_e32 v105, v96
	s_waitcnt lgkmcnt(0)
	v_pk_mul_f32 v[88:89], v[88:89], v[82:83]
	v_lshl_add_u64 v[90:91], s[20:21], 0, v[104:105]
	v_add_f32_e32 v80, v86, v89
	v_mul_f32_e32 v80, v88, v80
	v_add_co_u32_e32 v88, vcc, 0x2000, v90
	v_cvt_pk_bf16_f32 v80, v80, v96
	s_nop 1
	v_addc_co_u32_e32 v89, vcc, 0, v91, vcc
	global_store_short v[88:89], v80, off
	s_add_i32 s20, s33, 4
	s_cmpk_gt_i32 s20, 0x100f
	s_cbranch_scc0 .LBB0_600

; DEVI float bf2f(bf16_t v) { return __uint_as_float(((unsigned)v) << 16); }
; DEVI bf16_t f2bf(float f) { return (bf16_t)(pk_bf16(f, 0.f) & 0xffffu); }
; DEVI float sigmoidf_(float x) { return __builtin_amdgcn_rcpf(1.0f + __builtin_amdgcn_exp2f(-x * LOG2E)); }
; __device__ __forceinline__ void rglru_item8(const Params& p, unsigned char* lds, int item) {
;     ...
;         const float hv = Lk[k] + Pk[k] * hin; const int t = 64 * ti + 8 * seg + k;
;         if (k == 7 && seg == 7) hst[(cur ^ 1) * 64 + j] = hv;
;         if (t < T) { bf16_t* gp = Z + (size_t)(b * T + t) * LDZE + 4096 + g * 128 + h2 * 64 + j; const float x = bf2f(gbv[k]);
;           const float ge = x * sigmoidf_(1.5957691216057308f * (x + 0.044715f * x * x * x)); *gp = f2bf(hv * ge); }
.LBB0_617:
	v_lshlrev_b32_e32 v82, 16, v126
	v_mul_f32_e32 v80, 0x3d372713, v82
	v_mul_f32_e32 v80, v80, v82
	v_fma_f32 v80, v80, v82, v82
	v_mul_f32_e32 v80, 0x3fcc422a, v80
	v_mul_f32_e32 v80, 0xbfb8aa3b, v80
	v_exp_f32_e32 v80, v80
	s_nop 0
	v_add_f32_e32 v80, 1.0, v80
	v_rcp_f32_e32 v84, v80
	s_nop 0
	s_add_u32 s20, s98, 0xc800
	s_addc_u32 s21, s99, 0
	v_mov_b32_e32 v105, v96
	s_waitcnt lgkmcnt(0)
	v_pk_mul_f32 v[84:85], v[84:85], v[82:83]
	v_lshl_add_u64 v[86:87], s[20:21], 0, v[104:105]
	v_add_f32_e32 v80, v183, v85
	v_mul_f32_e32 v80, v84, v80
	v_add_co_u32_e32 v84, vcc, 0x2000, v86
	v_cvt_pk_bf16_f32 v80, v80, v96
	s_nop 1
	v_addc_co_u32_e32 v85, vcc, 0, v87, vcc
	global_store_short v[84:85], v80, off
	s_add_i32 s20, s33, 6
	s_cmpk_gt_i32 s20, 0x100f
	s_cbranch_scc0 .LBB0_602
	s_branch .LBB0_603

; DEVI unsigned pk_bf16(float lo, float hi) { unsigned r; asm("v_cvt_pk_bf16_f32 %0, %1, %2" : "=v"(r) : "v"(lo), "v"(hi)); return r; }
; DEVI float bf_lo(unsigned u) { return __uint_as_float(u << 16); }
; DEVI float bf_hi(unsigned u) { return __uint_as_float(u & 0xffff0000u); }
; #define LBAR() do { asm volatile("s_waitcnt lgkmcnt(0)" ::: "memory"); __builtin_amdgcn_s_barrier(); asm volatile("" ::: "memory"); } while (0)
; __device__ __forceinline__ void rglru_item8(const Params& p, unsigned char* lds, int item) {
;     ...
;     LBAR();
; #pragma unroll
;     for (int i = 0; i < 2; ++i) *(uint4*)(raw + (3 + prow + 32 * i) * 136 + pch * 8) = rx[i];
;     LBAR();
;     {
;       const int tr = tid >> 3, cp = tid & 7;
; #pragma unroll
;       for (int c8 = 0; c8 < 2; ++c8) {
;         const int c0 = cp * 16 + c8 * 8; float o[8];
; #pragma unroll
;         for (int j = 0; j < 8; ++j) o[j] = cw[512 + c0 + j];
; #pragma unroll
;         for (int k = 0; k < 4; ++k) { const uint4 xv = *(const uint4*)(raw + (tr + k) * 136 + c0); const float* wp = cw + k * 128 + c0;
;           o[0] += wp[0] * bf_lo(xv.x); o[1] += wp[1] * bf_hi(xv.x); o[2] += wp[2] * bf_lo(xv.y); o[3] += wp[3] * bf_hi(xv.y);
;           o[4] += wp[4] * bf_lo(xv.z); o[5] += wp[5] * bf_hi(xv.z); o[6] += wp[6] * bf_lo(xv.w); o[7] += wp[7] * bf_hi(xv.w); }
;         *(uint4*)(xcA + tr * 136 + c0) = make_uint4(pk_bf16(o[0], o[1]), pk_bf16(o[2], o[3]), pk_bf16(o[4], o[5]), pk_bf16(o[6], o[7]));
;         if ((cp >> 2) == h2) {
; #pragma unroll
;           for (int j = 0; j < 8; ++j) xcF[tr * 65 + (c0 - 64 * h2) + j] = o[j]; }
;       }
.LBB0_636:
	s_xor_b32 s62, s92, 1
	s_cmp_gt_u32 s88, 64
	s_cbranch_scc1 .LBB0_541
	s_waitcnt lgkmcnt(0)
	s_barrier
	ds_write_b128 v140, v[72:75] offset:816
	ds_write_b128 v140, v[76:79] offset:9520
	s_waitcnt lgkmcnt(0)
	s_barrier
	ds_read_b128 v[216:219], v142
	ds_read_b128 v[220:223], v142 offset:272
	ds_read_b128 v[224:227], v142 offset:544
	ds_read_b128 v[228:231], v142 offset:816
	ds_read_b128 v[184:187], v141
	ds_read_b128 v[188:191], v141 offset:16
	ds_read_b128 v[192:195], v141 offset:512
	ds_read_b128 v[196:199], v141 offset:528
	ds_read_b128 v[200:203], v141 offset:1024
	ds_read_b128 v[204:207], v141 offset:1040
	ds_read_b128 v[208:211], v141 offset:1536
	ds_read_b128 v[80:83], v141 offset:1552
	ds_read_b128 v[84:87], v141 offset:2048
	ds_read_b128 v[88:91], v141 offset:2064
	ds_read_b128 v[232:235], v142 offset:16
	ds_read_b128 v[236:239], v142 offset:288
	ds_read_b128 v[240:243], v142 offset:560
	ds_read_b128 v[244:247], v142 offset:832
	s_waitcnt lgkmcnt(4)
	v_lshlrev_b32_e32 v250, 16, v216
	v_and_b32_e32 v251, 0xffff0000, v216
	v_pk_fma_f32 v[92:93], v[184:185], v[250:251], v[84:85]
	v_lshlrev_b32_e32 v250, 16, v220
	v_and_b32_e32 v251, 0xffff0000, v220
	v_pk_fma_f32 v[92:93], v[192:193], v[250:251], v[92:93]
	v_lshlrev_b32_e32 v250, 16, v224
	v_and_b32_e32 v251, 0xffff0000, v224
	v_pk_fma_f32 v[92:93], v[200:201], v[250:251], v[92:93]
	v_lshlrev_b32_e32 v250, 16, v228
	v_and_b32_e32 v251, 0xffff0000, v228
	v_pk_fma_f32 v[92:93], v[208:209], v[250:251], v[92:93]
	v_lshlrev_b32_e32 v250, 16, v217
	v_and_b32_e32 v251, 0xffff0000, v217
	v_pk_fma_f32 v[94:95], v[186:187], v[250:251], v[86:87]
	v_lshlrev_b32_e32 v250, 16, v221
	v_and_b32_e32 v251, 0xffff0000, v221
	v_pk_fma_f32 v[94:95], v[194:195], v[250:251], v[94:95]
	v_lshlrev_b32_e32 v250, 16, v225
	v_and_b32_e32 v251, 0xffff0000, v225
	v_pk_fma_f32 v[94:95], v[202:203], v[250:251], v[94:95]
	v_lshlrev_b32_e32 v250, 16, v229
	v_and_b32_e32 v251, 0xffff0000, v229
	v_pk_fma_f32 v[94:95], v[210:211], v[250:251], v[94:95]
	v_lshlrev_b32_e32 v250, 16, v218
	v_and_b32_e32 v251, 0xffff0000, v218
	v_pk_fma_f32 v[106:107], v[188:189], v[250:251], v[88:89]
	v_lshlrev_b32_e32 v250, 16, v222
	v_and_b32_e32 v251, 0xffff0000, v222
	v_pk_fma_f32 v[106:107], v[196:197], v[250:251], v[106:107]
	v_lshlrev_b32_e32 v250, 16, v226
	v_and_b32_e32 v251, 0xffff0000, v226
	v_pk_fma_f32 v[106:107], v[204:205], v[250:251], v[106:107]
	v_lshlrev_b32_e32 v250, 16, v230
	v_and_b32_e32 v251, 0xffff0000, v230
	v_pk_fma_f32 v[106:107], v[80:81], v[250:251], v[106:107]
	v_lshlrev_b32_e32 v250, 16, v219
	v_and_b32_e32 v251, 0xffff0000, v219
	v_pk_fma_f32 v[248:249], v[190:191], v[250:251], v[90:91]
	v_lshlrev_b32_e32 v250, 16, v223
	v_and_b32_e32 v251, 0xffff0000, v223
	v_pk_fma_f32 v[248:249], v[198:199], v[250:251], v[248:249]
	v_lshlrev_b32_e32 v250, 16, v227
	v_and_b32_e32 v251, 0xffff0000, v227
	v_pk_fma_f32 v[248:249], v[206:207], v[250:251], v[248:249]
	v_lshlrev_b32_e32 v250, 16, v231
	v_and_b32_e32 v251, 0xffff0000, v231
	v_pk_fma_f32 v[248:249], v[82:83], v[250:251], v[248:249]
	v_cvt_pk_bf16_f32 v88, v92, v93
	v_cvt_pk_bf16_f32 v89, v94, v95
	v_cvt_pk_bf16_f32 v90, v106, v107
	v_cvt_pk_bf16_f32 v91, v248, v249
	ds_write_b128 v142, v[88:91] offset:18224
	s_and_saveexec_b64 s[40:41], s[2:3]
	s_cbranch_execz .Lrgc_b1
	v_add_u32_e32 v252, 0x8b30, v143
	ds_write2_b32 v252, v92, v93 offset1:1
	v_add_u32_e32 v252, 0x8b38, v143
	ds_write2_b32 v252, v94, v95 offset1:1
	v_add_u32_e32 v252, 0x8b40, v143
	ds_write2_b32 v252, v106, v107 offset1:1
	v_add_u32_e32 v252, 0x8b48, v143
	ds_write2_b32 v252, v248, v249 offset1:1
.Lrgc_b1:
	s_or_b64 exec, exec, s[40:41]
	ds_read_b128 v[184:187], v144
	ds_read_b128 v[188:191], v144 offset:16
	ds_read_b128 v[192:195], v144 offset:512
	ds_read_b128 v[196:199], v144 offset:528
	ds_read_b128 v[200:203], v144 offset:1024
	ds_read_b128 v[204:207], v144 offset:1040
	ds_read_b128 v[208:211], v144 offset:1536
	ds_read_b128 v[80:83], v144 offset:1552
	ds_read_b128 v[84:87], v144 offset:2048
	ds_read_b128 v[88:91], v141 offset:2096
	s_waitcnt lgkmcnt(0)
	v_lshlrev_b32_e32 v250, 16, v232
	v_and_b32_e32 v251, 0xffff0000, v232
	v_pk_fma_f32 v[92:93], v[184:185], v[250:251], v[84:85]
	v_lshlrev_b32_e32 v250, 16, v236
	v_and_b32_e32 v251, 0xffff0000, v236
	v_pk_fma_f32 v[92:93], v[192:193], v[250:251], v[92:93]
	v_lshlrev_b32_e32 v250, 16, v240
	v_and_b32_e32 v251, 0xffff0000, v240
	v_pk_fma_f32 v[92:93], v[200:201], v[250:251], v[92:93]
	v_lshlrev_b32_e32 v250, 16, v244
	v_and_b32_e32 v251, 0xffff0000, v244
	v_pk_fma_f32 v[92:93], v[208:209], v[250:251], v[92:93]
	v_lshlrev_b32_e32 v250, 16, v233
	v_and_b32_e32 v251, 0xffff0000, v233
	v_pk_fma_f32 v[94:95], v[186:187], v[250:251], v[86:87]
	v_lshlrev_b32_e32 v250, 16, v237
	v_and_b32_e32 v251, 0xffff0000, v237
	v_pk_fma_f32 v[94:95], v[194:195], v[250:251], v[94:95]
	v_lshlrev_b32_e32 v250, 16, v241
	v_and_b32_e32 v251, 0xffff0000, v241
	v_pk_fma_f32 v[94:95], v[202:203], v[250:251], v[94:95]
	v_lshlrev_b32_e32 v250, 16, v245
	v_and_b32_e32 v251, 0xffff0000, v245
	v_pk_fma_f32 v[94:95], v[210:211], v[250:251], v[94:95]
	v_lshlrev_b32_e32 v250, 16, v234
	v_and_b32_e32 v251, 0xffff0000, v234
	v_pk_fma_f32 v[106:107], v[188:189], v[250:251], v[88:89]
	v_lshlrev_b32_e32 v250, 16, v238
	v_and_b32_e32 v251, 0xffff0000, v238
	v_pk_fma_f32 v[106:107], v[196:197], v[250:251], v[106:107]
	v_lshlrev_b32_e32 v250, 16, v242
	v_and_b32_e32 v251, 0xffff0000, v242
	v_pk_fma_f32 v[106:107], v[204:205], v[250:251], v[106:107]
	v_lshlrev_b32_e32 v250, 16, v246
	v_and_b32_e32 v251, 0xffff0000, v246
	v_pk_fma_f32 v[106:107], v[80:81], v[250:251], v[106:107]
	v_lshlrev_b32_e32 v250, 16, v235
	v_and_b32_e32 v251, 0xffff0000, v235
	v_pk_fma_f32 v[248:249], v[190:191], v[250:251], v[90:91]
	v_lshlrev_b32_e32 v250, 16, v239
	v_and_b32_e32 v251, 0xffff0000, v239
	v_pk_fma_f32 v[248:249], v[198:199], v[250:251], v[248:249]
	v_lshlrev_b32_e32 v250, 16, v243
	v_and_b32_e32 v251, 0xffff0000, v243
	v_pk_fma_f32 v[248:249], v[206:207], v[250:251], v[248:249]
	v_lshlrev_b32_e32 v250, 16, v247
	v_and_b32_e32 v251, 0xffff0000, v247
	v_pk_fma_f32 v[248:249], v[82:83], v[250:251], v[248:249]
	v_cvt_pk_bf16_f32 v88, v92, v93
	v_cvt_pk_bf16_f32 v89, v94, v95
	v_cvt_pk_bf16_f32 v90, v106, v107
	v_cvt_pk_bf16_f32 v91, v248, v249
	ds_write_b128 v142, v[88:91] offset:18240
	s_and_saveexec_b64 s[40:41], s[2:3]
	s_cbranch_execz .LBB0_641
	v_add_u32_e32 v252, 0x8b50, v143
	ds_write2_b32 v252, v92, v93 offset1:1
	v_add_u32_e32 v252, 0x8b58, v143
	ds_write2_b32 v252, v94, v95 offset1:1
	v_add_u32_e32 v252, 0x8b60, v143
	ds_write2_b32 v252, v106, v107 offset1:1
	v_add_u32_e32 v252, 0x8b68, v143
	ds_write2_b32 v252, v248, v249 offset1:1

; DEVI float bf2f(bf16_t v) { return __uint_as_float(((unsigned)v) << 16); }
; DEVI bf16_t f2bf(float f) { return (bf16_t)(pk_bf16(f, 0.f) & 0xffffu); }
; DEVI float sigmoidf_(float x) { return __builtin_amdgcn_rcpf(1.0f + __builtin_amdgcn_exp2f(-x * LOG2E)); }
; __device__ __forceinline__ void rglru_item8(const Params& p, unsigned char* lds, int item) {
;     ...
;         const float hv = Lk[k] + Pk[k] * hin; const int t = 64 * ti + 8 * seg + k;
;         if (k == 7 && seg == 7) hst[(cur ^ 1) * 64 + j] = hv;
;         if (t < T) { bf16_t* gp = Z + (size_t)(b * T + t) * LDZE + 4096 + g * 128 + h2 * 64 + j; const float x = bf2f(gbv[k]);
;           const float ge = x * sigmoidf_(1.5957691216057308f * (x + 0.044715f * x * x * x)); *gp = f2bf(hv * ge); }
.LBB0_690:
	v_lshlrev_b32_e32 v82, 16, v127
	v_mul_f32_e32 v105, 0x3d372713, v82
	v_mul_f32_e32 v105, v105, v82
	v_fma_f32 v105, v105, v82, v82
	v_mul_f32_e32 v105, 0x3fcc422a, v105
	v_mul_f32_e32 v105, 0xbfb8aa3b, v105
	v_exp_f32_e32 v105, v105
	s_nop 0
	v_add_f32_e32 v105, 1.0, v105
	v_rcp_f32_e32 v182, v105
	s_nop 0
	s_add_u32 s6, s98, 0xa0000
	v_mov_b32_e32 v183, v80
	s_addc_u32 s7, s99, 0
	v_mov_b32_e32 v105, v96
	s_waitcnt lgkmcnt(0)
	v_pk_mul_f32 v[182:183], v[182:183], v[82:83]
	v_lshl_add_u64 v[184:185], s[6:7], 0, v[104:105]
	v_add_f32_e32 v80, v92, v183
	v_mul_f32_e32 v80, v182, v80
	v_add_co_u32_e32 v182, vcc, 0x2000, v184
	v_cvt_pk_bf16_f32 v80, v80, v96
	s_nop 1
	v_addc_co_u32_e32 v183, vcc, 0, v185, vcc
	global_store_short v[182:183], v80, off
	s_add_i32 s6, s33, 0x41
	s_cmpk_gt_i32 s6, 0x100f
	s_cbranch_scc0 .LBB0_706

; DEVI float bf2f(bf16_t v) { return __uint_as_float(((unsigned)v) << 16); }
; DEVI bf16_t f2bf(float f) { return (bf16_t)(pk_bf16(f, 0.f) & 0xffffu); }
; DEVI float sigmoidf_(float x) { return __builtin_amdgcn_rcpf(1.0f + __builtin_amdgcn_exp2f(-x * LOG2E)); }
; __device__ __forceinline__ void rglru_item8(const Params& p, unsigned char* lds, int item) {
;     ...
;         const float hv = Lk[k] + Pk[k] * hin; const int t = 64 * ti + 8 * seg + k;
;         if (k == 7 && seg == 7) hst[(cur ^ 1) * 64 + j] = hv;
;         if (t < T) { bf16_t* gp = Z + (size_t)(b * T + t) * LDZE + 4096 + g * 128 + h2 * 64 + j; const float x = bf2f(gbv[k]);
;           const float ge = x * sigmoidf_(1.5957691216057308f * (x + 0.044715f * x * x * x)); *gp = f2bf(hv * ge); }
.LBB0_692:
	v_lshlrev_b32_e32 v82, 16, v132
	v_mul_f32_e32 v80, 0x3d372713, v82
	v_mul_f32_e32 v80, v80, v82
	v_fma_f32 v80, v80, v82, v82
	v_mul_f32_e32 v80, 0x3fcc422a, v80
	v_mul_f32_e32 v80, 0xbfb8aa3b, v80
	v_exp_f32_e32 v80, v80
	s_nop 0
	v_add_f32_e32 v80, 1.0, v80
	v_rcp_f32_e32 v90, v80
	s_nop 0
	s_add_u32 s6, s98, 0xa5000
	s_addc_u32 s7, s99, 0
	v_mov_b32_e32 v105, v96
	s_waitcnt lgkmcnt(0)
	v_pk_mul_f32 v[90:91], v[90:91], v[82:83]
	v_lshl_add_u64 v[92:93], s[6:7], 0, v[104:105]
	v_add_f32_e32 v80, v88, v91
	v_mul_f32_e32 v80, v90, v80
	v_add_co_u32_e32 v90, vcc, 0x2000, v92
	v_cvt_pk_bf16_f32 v80, v80, v96
	s_nop 1
	v_addc_co_u32_e32 v91, vcc, 0, v93, vcc
	global_store_short v[90:91], v80, off
	s_add_i32 s6, s33, 0x43
	s_cmpk_gt_i32 s6, 0x100f
	s_cbranch_scc0 .LBB0_708

; DEVI float bf2f(bf16_t v) { return __uint_as_float(((unsigned)v) << 16); }
; DEVI bf16_t f2bf(float f) { return (bf16_t)(pk_bf16(f, 0.f) & 0xffffu); }
; DEVI float sigmoidf_(float x) { return __builtin_amdgcn_rcpf(1.0f + __builtin_amdgcn_exp2f(-x * LOG2E)); }
; __device__ __forceinline__ void rglru_item8(const Params& p, unsigned char* lds, int item) {
;     ...
;         const float hv = Lk[k] + Pk[k] * hin; const int t = 64 * ti + 8 * seg + k;
;         if (k == 7 && seg == 7) hst[(cur ^ 1) * 64 + j] = hv;
;         if (t < T) { bf16_t* gp = Z + (size_t)(b * T + t) * LDZE + 4096 + g * 128 + h2 * 64 + j; const float x = bf2f(gbv[k]);
;           const float ge = x * sigmoidf_(1.5957691216057308f * (x + 0.044715f * x * x * x)); *gp = f2bf(hv * ge); }
.LBB0_694:
	v_lshlrev_b32_e32 v82, 16, v134
	v_mul_f32_e32 v80, 0x3d372713, v82
	v_mul_f32_e32 v80, v80, v82
	v_fma_f32 v80, v80, v82, v82
	v_mul_f32_e32 v80, 0x3fcc422a, v80
	v_mul_f32_e32 v80, 0xbfb8aa3b, v80
	v_exp_f32_e32 v80, v80
	s_nop 0
	v_add_f32_e32 v80, 1.0, v80
	v_rcp_f32_e32 v86, v80
	s_nop 0
	s_add_u32 s6, s98, 0xaa000
	s_addc_u32 s7, s99, 0
	v_mov_b32_e32 v105, v96
	s_waitcnt lgkmcnt(0)
	v_pk_mul_f32 v[86:87], v[86:87], v[82:83]
	v_lshl_add_u64 v[88:89], s[6:7], 0, v[104:105]
	v_add_f32_e32 v80, v84, v87
	v_mul_f32_e32 v80, v86, v80
	v_add_co_u32_e32 v86, vcc, 0x2000, v88
	v_cvt_pk_bf16_f32 v80, v80, v96
	s_nop 1
	v_addc_co_u32_e32 v87, vcc, 0, v89, vcc
	global_store_short v[86:87], v80, off
	s_add_i32 s6, s33, 0x45
	s_cmpk_gt_i32 s6, 0x100f
	s_cbranch_scc0 .LBB0_710

; DEVI float bf2f(bf16_t v) { return __uint_as_float(((unsigned)v) << 16); }
; DEVI bf16_t f2bf(float f) { return (bf16_t)(pk_bf16(f, 0.f) & 0xffffu); }
; DEVI float sigmoidf_(float x) { return __builtin_amdgcn_rcpf(1.0f + __builtin_amdgcn_exp2f(-x * LOG2E)); }
; __device__ __forceinline__ void rglru_item8(const Params& p, unsigned char* lds, int item) {
;     ...
;         const float hv = Lk[k] + Pk[k] * hin; const int t = 64 * ti + 8 * seg + k;
;         if (k == 7 && seg == 7) hst[(cur ^ 1) * 64 + j] = hv;
;         if (t < T) { bf16_t* gp = Z + (size_t)(b * T + t) * LDZE + 4096 + g * 128 + h2 * 64 + j; const float x = bf2f(gbv[k]);
;           const float ge = x * sigmoidf_(1.5957691216057308f * (x + 0.044715f * x * x * x)); *gp = f2bf(hv * ge); }
.LBB0_696:
	v_lshlrev_b32_e32 v82, 16, v136
	v_mul_f32_e32 v80, 0x3d372713, v82
	v_mul_f32_e32 v80, v80, v82
	v_fma_f32 v80, v80, v82, v82
	v_mul_f32_e32 v80, 0x3fcc422a, v80
	v_mul_f32_e32 v80, 0xbfb8aa3b, v80
	v_exp_f32_e32 v80, v80
	s_nop 0
	v_add_f32_e32 v80, 1.0, v80
	v_rcp_f32_e32 v80, v80
	s_nop 0
	s_add_u32 s6, s98, 0xaf000
	s_waitcnt lgkmcnt(0)
	v_pk_mul_f32 v[80:81], v[80:81], v[82:83]
	s_addc_u32 s7, s99, 0
	v_mov_b32_e32 v105, v96
	v_add_f32_e32 v81, v95, v81
	v_lshl_add_u64 v[84:85], s[6:7], 0, v[104:105]
	v_mul_f32_e32 v80, v80, v81
	v_cvt_pk_bf16_f32 v82, v80, v96
	v_add_co_u32_e32 v80, vcc, 0x2000, v84
	s_nop 1
	v_addc_co_u32_e32 v81, vcc, 0, v85, vcc
	global_store_short v[80:81], v82, off
	s_and_b64 vcc, exec, s[20:21]
	v_fmac_f32_e32 v94, v97, v83
	s_cbranch_vccz .LBB0_712

; DEVI float bf2f(bf16_t v) { return __uint_as_float(((unsigned)v) << 16); }
; DEVI bf16_t f2bf(float f) { return (bf16_t)(pk_bf16(f, 0.f) & 0xffffu); }
; DEVI float sigmoidf_(float x) { return __builtin_amdgcn_rcpf(1.0f + __builtin_amdgcn_exp2f(-x * LOG2E)); }
; __device__ __forceinline__ void rglru_item8(const Params& p, unsigned char* lds, int item) {
;     ...
;         const float hv = Lk[k] + Pk[k] * hin; const int t = 64 * ti + 8 * seg + k;
;         if (k == 7 && seg == 7) hst[(cur ^ 1) * 64 + j] = hv;
;         if (t < T) { bf16_t* gp = Z + (size_t)(b * T + t) * LDZE + 4096 + g * 128 + h2 * 64 + j; const float x = bf2f(gbv[k]);
;           const float ge = x * sigmoidf_(1.5957691216057308f * (x + 0.044715f * x * x * x)); *gp = f2bf(hv * ge); }
.LBB0_698:
	v_lshlrev_b32_e32 v82, 16, v138
	v_mul_f32_e32 v80, 0x3d372713, v82
	v_mul_f32_e32 v80, v80, v82
	v_fma_f32 v80, v80, v82, v82
	v_mul_f32_e32 v80, 0x3fcc422a, v80
	v_mul_f32_e32 v80, 0xbfb8aa3b, v80
	v_exp_f32_e32 v80, v80
	s_nop 0
	v_add_f32_e32 v80, 1.0, v80
	v_rcp_f32_e32 v83, v80
	s_add_u32 s6, s98, 0xb1800
	s_addc_u32 s7, s99, 0
	v_mov_b32_e32 v105, v96
	v_lshl_add_u64 v[80:81], s[6:7], 0, v[104:105]
	v_mul_f32_e32 v82, v83, v82
	v_add_co_u32_e32 v80, vcc, 0x2000, v80
	v_mul_f32_e32 v82, v82, v94
	s_nop 0
	v_addc_co_u32_e32 v81, vcc, 0, v81, vcc
	v_cvt_pk_bf16_f32 v82, v82, v96
	global_store_short v[80:81], v82, off
	s_andn2_b64 vcc, exec, s[40:41]
	s_cbranch_vccnz .LBB0_542
	s_branch .LBB0_714

; DEVI float bf2f(bf16_t v) { return __uint_as_float(((unsigned)v) << 16); }
; DEVI bf16_t f2bf(float f) { return (bf16_t)(pk_bf16(f, 0.f) & 0xffffu); }
; DEVI float sigmoidf_(float x) { return __builtin_amdgcn_rcpf(1.0f + __builtin_amdgcn_exp2f(-x * LOG2E)); }
; __device__ __forceinline__ void rglru_item8(const Params& p, unsigned char* lds, int item) {
;     ...
;         const float hv = Lk[k] + Pk[k] * hin; const int t = 64 * ti + 8 * seg + k;
;         if (k == 7 && seg == 7) hst[(cur ^ 1) * 64 + j] = hv;
;         if (t < T) { bf16_t* gp = Z + (size_t)(b * T + t) * LDZE + 4096 + g * 128 + h2 * 64 + j; const float x = bf2f(gbv[k]);
;           const float ge = x * sigmoidf_(1.5957691216057308f * (x + 0.044715f * x * x * x)); *gp = f2bf(hv * ge); }
.LBB0_706:
	v_lshlrev_b32_e32 v82, 16, v125
	v_mul_f32_e32 v80, 0x3d372713, v82
	v_mul_f32_e32 v80, v80, v82
	v_fma_f32 v80, v80, v82, v82
	v_mul_f32_e32 v80, 0x3fcc422a, v80
	v_mul_f32_e32 v80, 0xbfb8aa3b, v80
	v_exp_f32_e32 v80, v80
	s_nop 0
	v_add_f32_e32 v80, 1.0, v80
	v_rcp_f32_e32 v92, v80
	s_nop 0
	s_add_u32 s6, s98, 0xa2800
	s_addc_u32 s7, s99, 0
	v_mov_b32_e32 v105, v96
	s_waitcnt lgkmcnt(0)
	v_pk_mul_f32 v[92:93], v[92:93], v[82:83]
	v_lshl_add_u64 v[182:183], s[6:7], 0, v[104:105]
	v_add_f32_e32 v80, v90, v93
	v_mul_f32_e32 v80, v92, v80
	v_add_co_u32_e32 v92, vcc, 0x2000, v182
	v_cvt_pk_bf16_f32 v80, v80, v96
	s_nop 1
	v_addc_co_u32_e32 v93, vcc, 0, v183, vcc
	global_store_short v[92:93], v80, off
	s_add_i32 s6, s33, 0x42
	s_cmpk_gt_i32 s6, 0x100f
	s_cbranch_scc0 .LBB0_692

; DEVI float bf2f(bf16_t v) { return __uint_as_float(((unsigned)v) << 16); }
; DEVI bf16_t f2bf(float f) { return (bf16_t)(pk_bf16(f, 0.f) & 0xffffu); }
; DEVI float sigmoidf_(float x) { return __builtin_amdgcn_rcpf(1.0f + __builtin_amdgcn_exp2f(-x * LOG2E)); }
; __device__ __forceinline__ void rglru_item8(const Params& p, unsigned char* lds, int item) {
;     ...
;         const float hv = Lk[k] + Pk[k] * hin; const int t = 64 * ti + 8 * seg + k;
;         if (k == 7 && seg == 7) hst[(cur ^ 1) * 64 + j] = hv;
;         if (t < T) { bf16_t* gp = Z + (size_t)(b * T + t) * LDZE + 4096 + g * 128 + h2 * 64 + j; const float x = bf2f(gbv[k]);
;           const float ge = x * sigmoidf_(1.5957691216057308f * (x + 0.044715f * x * x * x)); *gp = f2bf(hv * ge); }
.LBB0_708:
	v_lshlrev_b32_e32 v82, 16, v130
	v_mul_f32_e32 v80, 0x3d372713, v82
	v_mul_f32_e32 v80, v80, v82
	v_fma_f32 v80, v80, v82, v82
	v_mul_f32_e32 v80, 0x3fcc422a, v80
	v_mul_f32_e32 v80, 0xbfb8aa3b, v80
	v_exp_f32_e32 v80, v80
	s_nop 0
	v_add_f32_e32 v80, 1.0, v80
	v_rcp_f32_e32 v88, v80
	s_nop 0
	s_add_u32 s6, s98, 0xa7800
	s_addc_u32 s7, s99, 0
	v_mov_b32_e32 v105, v96
	s_waitcnt lgkmcnt(0)
	v_pk_mul_f32 v[88:89], v[88:89], v[82:83]
	v_lshl_add_u64 v[90:91], s[6:7], 0, v[104:105]
	v_add_f32_e32 v80, v86, v89
	v_mul_f32_e32 v80, v88, v80
	v_add_co_u32_e32 v88, vcc, 0x2000, v90
	v_cvt_pk_bf16_f32 v80, v80, v96
	s_nop 1
	v_addc_co_u32_e32 v89, vcc, 0, v91, vcc
	global_store_short v[88:89], v80, off
	s_add_i32 s6, s33, 0x44
	s_cmpk_gt_i32 s6, 0x100f
	s_cbranch_scc0 .LBB0_694

; DEVI float bf2f(bf16_t v) { return __uint_as_float(((unsigned)v) << 16); }
; DEVI bf16_t f2bf(float f) { return (bf16_t)(pk_bf16(f, 0.f) & 0xffffu); }
; DEVI float sigmoidf_(float x) { return __builtin_amdgcn_rcpf(1.0f + __builtin_amdgcn_exp2f(-x * LOG2E)); }
; __device__ __forceinline__ void rglru_item8(const Params& p, unsigned char* lds, int item) {
;     ...
;         const float hv = Lk[k] + Pk[k] * hin; const int t = 64 * ti + 8 * seg + k;
;         if (k == 7 && seg == 7) hst[(cur ^ 1) * 64 + j] = hv;
;         if (t < T) { bf16_t* gp = Z + (size_t)(b * T + t) * LDZE + 4096 + g * 128 + h2 * 64 + j; const float x = bf2f(gbv[k]);
;           const float ge = x * sigmoidf_(1.5957691216057308f * (x + 0.044715f * x * x * x)); *gp = f2bf(hv * ge); }
.LBB0_710:
	v_lshlrev_b32_e32 v82, 16, v135
	v_mul_f32_e32 v80, 0x3d372713, v82
	v_mul_f32_e32 v80, v80, v82
	v_fma_f32 v80, v80, v82, v82
	v_mul_f32_e32 v80, 0x3fcc422a, v80
	v_mul_f32_e32 v80, 0xbfb8aa3b, v80
	v_exp_f32_e32 v80, v80
	s_nop 0
	v_add_f32_e32 v80, 1.0, v80
	v_rcp_f32_e32 v84, v80
	s_nop 0
	s_add_u32 s6, s98, 0xac800
	s_addc_u32 s7, s99, 0
	v_mov_b32_e32 v105, v96
	s_waitcnt lgkmcnt(0)
	v_pk_mul_f32 v[84:85], v[84:85], v[82:83]
	v_lshl_add_u64 v[86:87], s[6:7], 0, v[104:105]
	v_add_f32_e32 v80, v107, v85
	v_mul_f32_e32 v80, v84, v80
	v_add_co_u32_e32 v84, vcc, 0x2000, v86
	v_cvt_pk_bf16_f32 v80, v80, v96
	s_nop 1
	v_addc_co_u32_e32 v85, vcc, 0, v87, vcc
	global_store_short v[84:85], v80, off
	s_add_i32 s6, s33, 0x46
	s_cmpk_gt_i32 s6, 0x100f
	s_cbranch_scc0 .LBB0_696

; __device__ __forceinline__ void rglru_item8(const Params& p, unsigned char* lds, int item) {
;     ...
;   auto loadgb = [&](int ti, bf16_t (&gbv)[8]) {
; #pragma unroll
;     for (int k = 0; k < 8; ++k) { const int t = 64 * ti + 8 * w + k; gbv[k] = t < T ? Z[(size_t)(b * T + t) * LDZE + 4096 + g * 128 + h2 * 64 + lane] : (bf16_t)0; }
;   };
.LBB0_714:
	s_add_i32 s6, s33, 0xc0
	v_mov_b32_e32 v125, 0
	s_cmpk_gt_i32 s6, 0x100f
	v_mov_b32_e32 v127, 0
	s_cbranch_scc1 .LBB0_716
	s_add_u32 s6, s98, 0x1e0000
	s_addc_u32 s7, s99, 0
	v_mov_b32_e32 v105, v96
	v_lshl_add_u64 v[80:81], s[6:7], 0, v[104:105]
	v_add_co_u32_e32 v80, vcc, 0x2000, v80
	s_nop 1
	v_addc_co_u32_e32 v81, vcc, 0, v81, vcc
	global_load_ushort v127, v[80:81], off
.LBB0_716:
	s_add_i32 s6, s33, 0xc1
	s_cmpk_gt_i32 s6, 0x100f
	s_cbranch_scc1 .LBB0_718
	s_add_u32 s6, s98, 0x1e2800
	s_addc_u32 s7, s99, 0
	v_mov_b32_e32 v105, v96
	v_lshl_add_u64 v[80:81], s[6:7], 0, v[104:105]
	v_add_co_u32_e32 v80, vcc, 0x2000, v80
	s_nop 1
	v_addc_co_u32_e32 v81, vcc, 0, v81, vcc
	global_load_ushort v125, v[80:81], off
.LBB0_718:
	s_add_i32 s6, s33, 0xc2
	v_mov_b32_e32 v130, 0
	s_cmpk_gt_i32 s6, 0x100f
	v_mov_b32_e32 v132, 0
	s_cbranch_scc1 .LBB0_720
	s_add_u32 s6, s98, 0x1e5000
	s_addc_u32 s7, s99, 0
	v_mov_b32_e32 v105, v96
	v_lshl_add_u64 v[80:81], s[6:7], 0, v[104:105]
	v_add_co_u32_e32 v80, vcc, 0x2000, v80
	s_nop 1
	v_addc_co_u32_e32 v81, vcc, 0, v81, vcc
	global_load_ushort v132, v[80:81], off
.LBB0_720:
	s_add_i32 s6, s33, 0xc3
	s_cmpk_gt_i32 s6, 0x100f
	s_cbranch_scc1 .LBB0_722
	s_add_u32 s6, s98, 0x1e7800
	s_addc_u32 s7, s99, 0
	v_mov_b32_e32 v105, v96
	v_lshl_add_u64 v[80:81], s[6:7], 0, v[104:105]
	v_add_co_u32_e32 v80, vcc, 0x2000, v80
	s_nop 1
	v_addc_co_u32_e32 v81, vcc, 0, v81, vcc
	global_load_ushort v130, v[80:81], off
.LBB0_722:
	s_add_i32 s6, s33, 0xc4
	v_mov_b32_e32 v135, 0
	s_cmpk_gt_i32 s6, 0x100f
	v_mov_b32_e32 v134, 0
	s_cbranch_scc1 .LBB0_724
	s_add_u32 s6, s98, 0x1ea000
	s_addc_u32 s7, s99, 0
	v_mov_b32_e32 v105, v96
	v_lshl_add_u64 v[80:81], s[6:7], 0, v[104:105]
	v_add_co_u32_e32 v80, vcc, 0x2000, v80
	s_nop 1
	v_addc_co_u32_e32 v81, vcc, 0, v81, vcc
	global_load_ushort v134, v[80:81], off
.LBB0_724:
	s_add_i32 s6, s33, 0xc5
	s_cmpk_gt_i32 s6, 0x100f
	s_cbranch_scc1 .LBB0_726
	s_add_u32 s6, s98, 0x1ec800
	s_addc_u32 s7, s99, 0
	v_mov_b32_e32 v105, v96
	v_lshl_add_u64 v[80:81], s[6:7], 0, v[104:105]
	v_add_co_u32_e32 v80, vcc, 0x2000, v80
	s_nop 1
	v_addc_co_u32_e32 v81, vcc, 0, v81, vcc
	global_load_ushort v135, v[80:81], off
.LBB0_726:
	s_add_i32 s6, s33, 0xc6
	v_mov_b32_e32 v138, 0
	s_cmpk_gt_i32 s6, 0x100f
	v_mov_b32_e32 v136, 0
	s_cbranch_scc1 .LBB0_728
	s_add_u32 s6, s98, 0x1ef000
	s_addc_u32 s7, s99, 0
	v_mov_b32_e32 v105, v96
	v_lshl_add_u64 v[80:81], s[6:7], 0, v[104:105]
	v_add_co_u32_e32 v80, vcc, 0x2000, v80
	s_nop 1
	v_addc_co_u32_e32 v81, vcc, 0, v81, vcc
	global_load_ushort v136, v[80:81], off
.LBB0_728:
	s_addk_i32 s33, 0xc7
	s_cmpk_gt_i32 s33, 0x100f
	s_cbranch_scc1 .LBB0_542
	s_add_u32 s6, s98, 0x1f1800
	s_addc_u32 s7, s99, 0
	v_mov_b32_e32 v105, v96
	v_lshl_add_u64 v[80:81], s[6:7], 0, v[104:105]
	v_add_co_u32_e32 v80, vcc, 0x2000, v80
	s_nop 1
	v_addc_co_u32_e32 v81, vcc, 0, v81, vcc
	global_load_ushort v138, v[80:81], off
	s_branch .LBB0_542
